# half-unit-only GEMM loops (P5 sample rows, P7-in-P6): 3 barriers per K-tile; barrier behind the never-run second MFMA segment removed, restage wait moved to end of the MFMA segment
# baseline (speedup 1.0000x reference)
.LBB0_902:
	s_add_i32 s78, s78, 2
	s_add_u32 s76, s76, 0x1c0000
	s_addc_u32 s77, s77, 0
	s_add_u32 s62, s62, 0x440000
	s_addc_u32 s63, s63, 0
	s_cmp_gt_u32 s78, 29
	s_cbranch_scc1 .LBB0_911
.LBB0_903:
	ds_read_b128 v[146:149], v225
	ds_read_b128 v[150:153], v225 offset:1024
	ds_read_b128 v[154:157], v225 offset:2048
	ds_read_b128 v[158:161], v225 offset:3072
	ds_read_b128 v[130:133], v227
	ds_read_b128 v[134:137], v227 offset:1024
	ds_read_b128 v[138:141], v227 offset:2048
	ds_read_b128 v[142:145], v227 offset:3072
	s_waitcnt lgkmcnt(0)
	ds_read_b128 v[174:177], v228
	ds_read_b128 v[190:193], v228 offset:1024
	ds_read_b128 v[170:173], v228 offset:2048
	ds_read_b128 v[186:189], v228 offset:3072
	ds_read_b128 v[166:169], v228 offset:4096
	ds_read_b128 v[182:185], v228 offset:5120
	ds_read_b128 v[162:165], v228 offset:6144
	ds_read_b128 v[178:181], v228 offset:7168
	s_waitcnt lgkmcnt(0)
	s_barrier
	v_mfma_f32_16x16x32_bf16 v[126:129], v[146:149], v[174:177], v[126:129]
	v_mfma_f32_16x16x32_bf16 v[122:125], v[154:157], v[174:177], v[122:125]
	v_mfma_f32_16x16x32_bf16 v[118:121], v[146:149], v[170:173], v[118:121]
	v_mfma_f32_16x16x32_bf16 v[114:117], v[154:157], v[170:173], v[114:117]
	v_mfma_f32_16x16x32_bf16 v[110:113], v[146:149], v[166:169], v[110:113]
	v_mfma_f32_16x16x32_bf16 v[106:109], v[154:157], v[166:169], v[106:109]
	v_mfma_f32_16x16x32_bf16 v[102:105], v[146:149], v[162:165], v[102:105]
	v_mfma_f32_16x16x32_bf16 v[98:101], v[154:157], v[162:165], v[98:101]
	v_mfma_f32_16x16x32_bf16 v[126:129], v[150:153], v[190:193], v[126:129]
	v_mfma_f32_16x16x32_bf16 v[122:125], v[158:161], v[190:193], v[122:125]
	v_mfma_f32_16x16x32_bf16 v[118:121], v[150:153], v[186:189], v[118:121]
	v_mfma_f32_16x16x32_bf16 v[114:117], v[158:161], v[186:189], v[114:117]
	v_mfma_f32_16x16x32_bf16 v[110:113], v[150:153], v[182:185], v[110:113]
	v_mfma_f32_16x16x32_bf16 v[106:109], v[158:161], v[182:185], v[106:109]
	v_mfma_f32_16x16x32_bf16 v[102:105], v[150:153], v[178:181], v[102:105]
	v_mfma_f32_16x16x32_bf16 v[98:101], v[158:161], v[178:181], v[98:101]
	v_mfma_f32_16x16x32_bf16 v[94:97], v[130:133], v[174:177], v[94:97]
	v_mfma_f32_16x16x32_bf16 v[90:93], v[138:141], v[174:177], v[90:93]
	v_mfma_f32_16x16x32_bf16 v[86:89], v[130:133], v[170:173], v[86:89]
	v_mfma_f32_16x16x32_bf16 v[82:85], v[138:141], v[170:173], v[82:85]
	v_mfma_f32_16x16x32_bf16 v[78:81], v[130:133], v[166:169], v[78:81]
	v_mfma_f32_16x16x32_bf16 v[74:77], v[138:141], v[166:169], v[74:77]
	v_mfma_f32_16x16x32_bf16 v[70:73], v[130:133], v[162:165], v[70:73]
	v_mfma_f32_16x16x32_bf16 v[66:69], v[138:141], v[162:165], v[66:69]
	v_mfma_f32_16x16x32_bf16 v[94:97], v[134:137], v[190:193], v[94:97]
	v_mfma_f32_16x16x32_bf16 v[90:93], v[142:145], v[190:193], v[90:93]
	v_mfma_f32_16x16x32_bf16 v[86:89], v[134:137], v[186:189], v[86:89]
	v_mfma_f32_16x16x32_bf16 v[82:85], v[142:145], v[186:189], v[82:85]
	v_mfma_f32_16x16x32_bf16 v[78:81], v[134:137], v[182:185], v[78:81]
	v_mfma_f32_16x16x32_bf16 v[74:77], v[142:145], v[182:185], v[74:77]
	v_mfma_f32_16x16x32_bf16 v[70:73], v[134:137], v[178:181], v[70:73]
	v_mfma_f32_16x16x32_bf16 v[66:69], v[142:145], v[178:181], v[66:69]
	s_waitcnt vmcnt(0)
	s_barrier
	v_cmp_ne_u32_e64 s[42:43], 1, v233
	s_andn2_b64 vcc, exec, s[44:45]
	s_cbranch_vccnz .LBB0_905
	ds_read_b128 v[174:177], v228 offset:16384
	ds_read_b128 v[190:193], v228 offset:17408
	ds_read_b128 v[170:173], v228 offset:18432
	ds_read_b128 v[186:189], v228 offset:19456
	ds_read_b128 v[166:169], v228 offset:20480
	ds_read_b128 v[182:185], v228 offset:21504
	ds_read_b128 v[162:165], v228 offset:22528
	ds_read_b128 v[178:181], v228 offset:23552
.LBB0_905:
	s_add_u32 s68, s0, s62
	s_addc_u32 s69, s1, s63
	s_add_u32 s70, s68, 0x440000
	s_addc_u32 s71, s69, 0
	s_cmp_eq_u32 s62, 0x3fc0000
	s_cselect_b64 s[72:73], -1, 0
	s_and_b64 s[68:69], s[72:73], exec
	s_cselect_b32 s69, s37, s77
	s_cselect_b32 s68, s75, s76
	s_mov_b32 m0, s9
	s_cselect_b32 s71, s35, s71
	s_cselect_b32 s70, s74, s70
	s_add_u32 s80, s68, 0x4000
	global_load_lds_dwordx4 v194, s[68:69]
	s_mov_b32 m0, s10
	s_addc_u32 s81, s69, 0
	global_load_lds_dwordx4 v196, s[68:69]
	s_mov_b32 m0, s11
	s_and_b64 vcc, exec, s[42:43]
	global_load_lds_dwordx4 v194, s[80:81]
	s_mov_b32 m0, s12
	s_nop 0
	global_load_lds_dwordx4 v196, s[80:81]
	s_mov_b32 m0, s8
	s_nop 0
	global_load_lds_dwordx4 v194, s[70:71]
	s_mov_b32 m0, s13
	s_nop 0
	global_load_lds_dwordx4 v196, s[70:71]
	s_waitcnt lgkmcnt(0)
	s_barrier
	s_cbranch_vccnz .LBB0_907
	s_waitcnt lgkmcnt(0)
	v_mfma_f32_16x16x32_bf16 v[62:65], v[146:149], v[174:177], v[62:65]
	v_mfma_f32_16x16x32_bf16 v[58:61], v[154:157], v[174:177], v[58:61]
	v_mfma_f32_16x16x32_bf16 v[54:57], v[146:149], v[170:173], v[54:57]
	v_mfma_f32_16x16x32_bf16 v[50:53], v[154:157], v[170:173], v[50:53]
	v_mfma_f32_16x16x32_bf16 v[46:49], v[146:149], v[166:169], v[46:49]
	v_mfma_f32_16x16x32_bf16 v[42:45], v[154:157], v[166:169], v[42:45]
	v_mfma_f32_16x16x32_bf16 v[38:41], v[146:149], v[162:165], v[38:41]
	v_mfma_f32_16x16x32_bf16 v[34:37], v[154:157], v[162:165], v[34:37]
	v_mfma_f32_16x16x32_bf16 v[62:65], v[150:153], v[190:193], v[62:65]
	v_mfma_f32_16x16x32_bf16 v[58:61], v[158:161], v[190:193], v[58:61]
	v_mfma_f32_16x16x32_bf16 v[54:57], v[150:153], v[186:189], v[54:57]
	v_mfma_f32_16x16x32_bf16 v[50:53], v[158:161], v[186:189], v[50:53]
	v_mfma_f32_16x16x32_bf16 v[46:49], v[150:153], v[182:185], v[46:49]
	v_mfma_f32_16x16x32_bf16 v[42:45], v[158:161], v[182:185], v[42:45]
	v_mfma_f32_16x16x32_bf16 v[38:41], v[150:153], v[178:181], v[38:41]
	v_mfma_f32_16x16x32_bf16 v[34:37], v[158:161], v[178:181], v[34:37]
	v_mfma_f32_16x16x32_bf16 v[30:33], v[130:133], v[174:177], v[30:33]
	v_mfma_f32_16x16x32_bf16 v[26:29], v[138:141], v[174:177], v[26:29]
	v_mfma_f32_16x16x32_bf16 v[22:25], v[130:133], v[170:173], v[22:25]
	v_mfma_f32_16x16x32_bf16 v[18:21], v[138:141], v[170:173], v[18:21]
	v_mfma_f32_16x16x32_bf16 v[14:17], v[130:133], v[166:169], v[14:17]
	v_mfma_f32_16x16x32_bf16 v[10:13], v[138:141], v[166:169], v[10:13]
	v_mfma_f32_16x16x32_bf16 v[6:9], v[130:133], v[162:165], v[6:9]
	v_mfma_f32_16x16x32_bf16 v[2:5], v[138:141], v[162:165], v[2:5]
	v_mfma_f32_16x16x32_bf16 v[30:33], v[134:137], v[190:193], v[30:33]
	v_mfma_f32_16x16x32_bf16 v[26:29], v[142:145], v[190:193], v[26:29]
	v_mfma_f32_16x16x32_bf16 v[22:25], v[134:137], v[186:189], v[22:25]
	v_mfma_f32_16x16x32_bf16 v[18:21], v[142:145], v[186:189], v[18:21]
	v_mfma_f32_16x16x32_bf16 v[14:17], v[134:137], v[182:185], v[14:17]
	v_mfma_f32_16x16x32_bf16 v[10:13], v[142:145], v[182:185], v[10:13]
	v_mfma_f32_16x16x32_bf16 v[6:9], v[134:137], v[178:181], v[6:9]
	v_mfma_f32_16x16x32_bf16 v[2:5], v[142:145], v[178:181], v[2:5]
.LBB0_907:
	s_and_b64 vcc, s[40:41], s[72:73]
	v_cndmask_b32_e64 v131, v209, 0, vcc
	v_cndmask_b32_e32 v130, v208, v198, vcc
	v_lshl_add_u64 v[234:235], s[70:71], 0, v[130:131]
	v_add_u32_e32 v130, 0x18000, v224
	v_add_u32_e32 v142, 0x1c000, v224
	ds_read_b128 v[146:149], v130
	ds_read_b128 v[150:153], v130 offset:1024
	ds_read_b128 v[154:157], v130 offset:2048
	ds_read_b128 v[158:161], v130 offset:3072
	ds_read_b128 v[130:133], v142
	ds_read_b128 v[134:137], v142 offset:1024
	ds_read_b128 v[138:141], v142 offset:2048
	ds_read_b128 v[142:145], v142 offset:3072
	s_waitcnt lgkmcnt(0)
	ds_read_b128 v[174:177], v228 offset:32768
	ds_read_b128 v[190:193], v228 offset:33792
	ds_read_b128 v[170:173], v228 offset:34816
	ds_read_b128 v[186:189], v228 offset:35840
	ds_read_b128 v[166:169], v228 offset:36864
	ds_read_b128 v[182:185], v228 offset:37888
	ds_read_b128 v[162:165], v228 offset:38912
	ds_read_b128 v[178:181], v228 offset:39936
	s_waitcnt lgkmcnt(0)
	s_barrier
	v_mfma_f32_16x16x32_bf16 v[126:129], v[146:149], v[174:177], v[126:129]
	v_mfma_f32_16x16x32_bf16 v[122:125], v[154:157], v[174:177], v[122:125]
	v_mfma_f32_16x16x32_bf16 v[118:121], v[146:149], v[170:173], v[118:121]
	v_mfma_f32_16x16x32_bf16 v[114:117], v[154:157], v[170:173], v[114:117]
	v_mfma_f32_16x16x32_bf16 v[110:113], v[146:149], v[166:169], v[110:113]
	v_mfma_f32_16x16x32_bf16 v[106:109], v[154:157], v[166:169], v[106:109]
	v_mfma_f32_16x16x32_bf16 v[102:105], v[146:149], v[162:165], v[102:105]
	v_mfma_f32_16x16x32_bf16 v[98:101], v[154:157], v[162:165], v[98:101]
	v_mfma_f32_16x16x32_bf16 v[126:129], v[150:153], v[190:193], v[126:129]
	v_mfma_f32_16x16x32_bf16 v[122:125], v[158:161], v[190:193], v[122:125]
	v_mfma_f32_16x16x32_bf16 v[118:121], v[150:153], v[186:189], v[118:121]
	v_mfma_f32_16x16x32_bf16 v[114:117], v[158:161], v[186:189], v[114:117]
	v_mfma_f32_16x16x32_bf16 v[110:113], v[150:153], v[182:185], v[110:113]
	v_mfma_f32_16x16x32_bf16 v[106:109], v[158:161], v[182:185], v[106:109]
	v_mfma_f32_16x16x32_bf16 v[102:105], v[150:153], v[178:181], v[102:105]
	v_mfma_f32_16x16x32_bf16 v[98:101], v[158:161], v[178:181], v[98:101]
	v_mfma_f32_16x16x32_bf16 v[94:97], v[130:133], v[174:177], v[94:97]
	v_mfma_f32_16x16x32_bf16 v[90:93], v[138:141], v[174:177], v[90:93]
	v_mfma_f32_16x16x32_bf16 v[86:89], v[130:133], v[170:173], v[86:89]
	v_mfma_f32_16x16x32_bf16 v[82:85], v[138:141], v[170:173], v[82:85]
	v_mfma_f32_16x16x32_bf16 v[78:81], v[130:133], v[166:169], v[78:81]
	v_mfma_f32_16x16x32_bf16 v[74:77], v[138:141], v[166:169], v[74:77]
	v_mfma_f32_16x16x32_bf16 v[70:73], v[130:133], v[162:165], v[70:73]
	v_mfma_f32_16x16x32_bf16 v[66:69], v[138:141], v[162:165], v[66:69]
	v_mfma_f32_16x16x32_bf16 v[94:97], v[134:137], v[190:193], v[94:97]
	v_mfma_f32_16x16x32_bf16 v[90:93], v[142:145], v[190:193], v[90:93]
	v_mfma_f32_16x16x32_bf16 v[86:89], v[134:137], v[186:189], v[86:89]
	v_mfma_f32_16x16x32_bf16 v[82:85], v[142:145], v[186:189], v[82:85]
	v_mfma_f32_16x16x32_bf16 v[78:81], v[134:137], v[182:185], v[78:81]
	v_mfma_f32_16x16x32_bf16 v[74:77], v[142:145], v[182:185], v[74:77]
	v_mfma_f32_16x16x32_bf16 v[70:73], v[134:137], v[178:181], v[70:73]
	v_mfma_f32_16x16x32_bf16 v[66:69], v[142:145], v[178:181], v[66:69]
	s_waitcnt vmcnt(0)
	s_barrier
	s_and_b64 vcc, exec, s[42:43]
	s_cbranch_vccnz .LBB0_909
	ds_read_b128 v[174:177], v228 offset:49152
	ds_read_b128 v[190:193], v228 offset:50176
	ds_read_b128 v[170:173], v228 offset:51200
	ds_read_b128 v[186:189], v228 offset:52224
	ds_read_b128 v[166:169], v228 offset:53248
	ds_read_b128 v[182:185], v228 offset:54272
	ds_read_b128 v[162:165], v228 offset:55296
	ds_read_b128 v[178:181], v228 offset:56320
.LBB0_909:
	s_add_u32 s72, s68, 0xe0000
	s_addc_u32 s73, s69, 0
	s_add_u32 s70, s70, 0x220000
	s_addc_u32 s71, s71, 0
	s_mov_b32 m0, s16
	s_add_u32 s68, s68, 0xe4000
	global_load_lds_dwordx4 v194, s[72:73]
	s_mov_b32 m0, s17
	s_addc_u32 s69, s69, 0
	global_load_lds_dwordx4 v196, s[72:73]
	s_mov_b32 m0, s54
	s_and_b64 vcc, exec, s[42:43]
	global_load_lds_dwordx4 v194, s[68:69]
	s_mov_b32 m0, s55
	s_nop 0
	global_load_lds_dwordx4 v196, s[68:69]
	s_mov_b32 m0, s23
	s_nop 0
	global_load_lds_dwordx4 v194, s[70:71]
	s_mov_b32 m0, s31
	s_nop 0
	global_load_lds_dwordx4 v196, s[70:71]
	s_waitcnt lgkmcnt(0)
	s_barrier
	s_cbranch_vccnz .LBB0_902
	s_waitcnt lgkmcnt(0)
	v_mfma_f32_16x16x32_bf16 v[62:65], v[146:149], v[174:177], v[62:65]
	v_mfma_f32_16x16x32_bf16 v[58:61], v[154:157], v[174:177], v[58:61]
	v_mfma_f32_16x16x32_bf16 v[54:57], v[146:149], v[170:173], v[54:57]
	v_mfma_f32_16x16x32_bf16 v[50:53], v[154:157], v[170:173], v[50:53]
	v_mfma_f32_16x16x32_bf16 v[46:49], v[146:149], v[166:169], v[46:49]
	v_mfma_f32_16x16x32_bf16 v[42:45], v[154:157], v[166:169], v[42:45]
	v_mfma_f32_16x16x32_bf16 v[38:41], v[146:149], v[162:165], v[38:41]
	v_mfma_f32_16x16x32_bf16 v[34:37], v[154:157], v[162:165], v[34:37]
	v_mfma_f32_16x16x32_bf16 v[62:65], v[150:153], v[190:193], v[62:65]
	v_mfma_f32_16x16x32_bf16 v[58:61], v[158:161], v[190:193], v[58:61]
	v_mfma_f32_16x16x32_bf16 v[54:57], v[150:153], v[186:189], v[54:57]
	v_mfma_f32_16x16x32_bf16 v[50:53], v[158:161], v[186:189], v[50:53]
	v_mfma_f32_16x16x32_bf16 v[46:49], v[150:153], v[182:185], v[46:49]
	v_mfma_f32_16x16x32_bf16 v[42:45], v[158:161], v[182:185], v[42:45]
	v_mfma_f32_16x16x32_bf16 v[38:41], v[150:153], v[178:181], v[38:41]
	v_mfma_f32_16x16x32_bf16 v[34:37], v[158:161], v[178:181], v[34:37]
	v_mfma_f32_16x16x32_bf16 v[30:33], v[130:133], v[174:177], v[30:33]
	v_mfma_f32_16x16x32_bf16 v[26:29], v[138:141], v[174:177], v[26:29]
	v_mfma_f32_16x16x32_bf16 v[22:25], v[130:133], v[170:173], v[22:25]
	v_mfma_f32_16x16x32_bf16 v[18:21], v[138:141], v[170:173], v[18:21]
	v_mfma_f32_16x16x32_bf16 v[14:17], v[130:133], v[166:169], v[14:17]
	v_mfma_f32_16x16x32_bf16 v[10:13], v[138:141], v[166:169], v[10:13]
	v_mfma_f32_16x16x32_bf16 v[6:9], v[130:133], v[162:165], v[6:9]
	v_mfma_f32_16x16x32_bf16 v[2:5], v[138:141], v[162:165], v[2:5]
	v_mfma_f32_16x16x32_bf16 v[30:33], v[134:137], v[190:193], v[30:33]
	v_mfma_f32_16x16x32_bf16 v[26:29], v[142:145], v[190:193], v[26:29]
	v_mfma_f32_16x16x32_bf16 v[22:25], v[134:137], v[186:189], v[22:25]
	v_mfma_f32_16x16x32_bf16 v[18:21], v[142:145], v[186:189], v[18:21]
	v_mfma_f32_16x16x32_bf16 v[14:17], v[134:137], v[182:185], v[14:17]
	v_mfma_f32_16x16x32_bf16 v[10:13], v[142:145], v[182:185], v[10:13]
	v_mfma_f32_16x16x32_bf16 v[6:9], v[134:137], v[178:181], v[6:9]
	v_mfma_f32_16x16x32_bf16 v[2:5], v[142:145], v[178:181], v[2:5]
	s_branch .LBB0_902

.LBB0_1288:
	s_add_i32 s67, s67, 2
	s_add_u32 s62, s62, 0x80000
	s_addc_u32 s63, s63, 0
	s_add_u32 s48, s48, 0x440000
	s_addc_u32 s49, s49, 0
	s_cmp_gt_u32 s67, 29
	s_cbranch_scc1 .LBB0_1297
.LBB0_1289:
	v_add_u32_e32 v142, 0x14000, v229
	ds_read_b128 v[146:149], v230
	ds_read_b128 v[150:153], v230 offset:1024
	ds_read_b128 v[154:157], v230 offset:2048
	ds_read_b128 v[158:161], v230 offset:3072
	ds_read_b128 v[130:133], v142
	ds_read_b128 v[134:137], v142 offset:1024
	ds_read_b128 v[138:141], v142 offset:2048
	ds_read_b128 v[142:145], v142 offset:3072
	s_waitcnt lgkmcnt(0)
	ds_read_b128 v[174:177], v231
	ds_read_b128 v[190:193], v231 offset:1024
	ds_read_b128 v[170:173], v231 offset:2048
	ds_read_b128 v[186:189], v231 offset:3072
	ds_read_b128 v[166:169], v231 offset:4096
	ds_read_b128 v[182:185], v231 offset:5120
	ds_read_b128 v[162:165], v231 offset:6144
	ds_read_b128 v[178:181], v231 offset:7168
	s_waitcnt lgkmcnt(0)
	s_barrier
	v_mfma_f32_16x16x32_bf16 v[126:129], v[146:149], v[174:177], v[126:129]
	v_mfma_f32_16x16x32_bf16 v[122:125], v[154:157], v[174:177], v[122:125]
	v_mfma_f32_16x16x32_bf16 v[118:121], v[146:149], v[170:173], v[118:121]
	v_mfma_f32_16x16x32_bf16 v[110:113], v[154:157], v[170:173], v[110:113]
	v_mfma_f32_16x16x32_bf16 v[102:105], v[146:149], v[166:169], v[102:105]
	v_mfma_f32_16x16x32_bf16 v[94:97], v[154:157], v[166:169], v[94:97]
	v_mfma_f32_16x16x32_bf16 v[86:89], v[146:149], v[162:165], v[86:89]
	v_mfma_f32_16x16x32_bf16 v[78:81], v[154:157], v[162:165], v[78:81]
	v_mfma_f32_16x16x32_bf16 v[126:129], v[150:153], v[190:193], v[126:129]
	v_mfma_f32_16x16x32_bf16 v[122:125], v[158:161], v[190:193], v[122:125]
	v_mfma_f32_16x16x32_bf16 v[118:121], v[150:153], v[186:189], v[118:121]
	v_mfma_f32_16x16x32_bf16 v[110:113], v[158:161], v[186:189], v[110:113]
	v_mfma_f32_16x16x32_bf16 v[102:105], v[150:153], v[182:185], v[102:105]
	v_mfma_f32_16x16x32_bf16 v[94:97], v[158:161], v[182:185], v[94:97]
	v_mfma_f32_16x16x32_bf16 v[86:89], v[150:153], v[178:181], v[86:89]
	v_mfma_f32_16x16x32_bf16 v[78:81], v[158:161], v[178:181], v[78:81]
	v_mfma_f32_16x16x32_bf16 v[114:117], v[130:133], v[174:177], v[114:117]
	v_mfma_f32_16x16x32_bf16 v[106:109], v[138:141], v[174:177], v[106:109]
	v_mfma_f32_16x16x32_bf16 v[98:101], v[130:133], v[170:173], v[98:101]
	v_mfma_f32_16x16x32_bf16 v[90:93], v[138:141], v[170:173], v[90:93]
	v_mfma_f32_16x16x32_bf16 v[82:85], v[130:133], v[166:169], v[82:85]
	v_mfma_f32_16x16x32_bf16 v[74:77], v[138:141], v[166:169], v[74:77]
	v_mfma_f32_16x16x32_bf16 v[70:73], v[130:133], v[162:165], v[70:73]
	v_mfma_f32_16x16x32_bf16 v[66:69], v[138:141], v[162:165], v[66:69]
	v_mfma_f32_16x16x32_bf16 v[114:117], v[134:137], v[190:193], v[114:117]
	v_mfma_f32_16x16x32_bf16 v[106:109], v[142:145], v[190:193], v[106:109]
	v_mfma_f32_16x16x32_bf16 v[98:101], v[134:137], v[186:189], v[98:101]
	v_mfma_f32_16x16x32_bf16 v[90:93], v[142:145], v[186:189], v[90:93]
	v_mfma_f32_16x16x32_bf16 v[82:85], v[134:137], v[182:185], v[82:85]
	v_mfma_f32_16x16x32_bf16 v[74:77], v[142:145], v[182:185], v[74:77]
	v_mfma_f32_16x16x32_bf16 v[70:73], v[134:137], v[178:181], v[70:73]
	v_mfma_f32_16x16x32_bf16 v[66:69], v[142:145], v[178:181], v[66:69]
	s_waitcnt vmcnt(0)
	s_barrier
	s_andn2_b64 s[42:43], exec, s[40:41]
	s_andn2_b64 vcc, exec, s[40:41]
	s_cbranch_vccnz .LBB0_1291
	ds_read_b128 v[174:177], v231 offset:16384
	ds_read_b128 v[190:193], v231 offset:17408
	ds_read_b128 v[170:173], v231 offset:18432
	ds_read_b128 v[186:189], v231 offset:19456
	ds_read_b128 v[166:169], v231 offset:20480
	ds_read_b128 v[182:185], v231 offset:21504
	ds_read_b128 v[162:165], v231 offset:22528
	ds_read_b128 v[178:181], v231 offset:23552
.LBB0_1291:
	s_add_u32 s52, s36, s48
	s_addc_u32 s53, s37, s49
	s_add_u32 s56, s52, 0x440000
	s_addc_u32 s57, s53, 0
	s_cmp_eq_u32 s48, 0x3fc0000
	s_cselect_b64 s[58:59], -1, 0
	s_and_b64 s[52:53], s[58:59], exec
	s_cselect_b32 s53, s31, s63
	s_cselect_b32 s52, s61, s62
	s_mov_b32 m0, s9
	s_cselect_b32 s57, s19, s57
	s_cselect_b32 s56, s29, s56
	s_add_u32 s68, s52, 0x4000
	global_load_lds_dwordx4 v194, s[52:53]
	s_mov_b32 m0, s10
	s_addc_u32 s69, s53, 0
	global_load_lds_dwordx4 v196, s[52:53]
	s_mov_b32 m0, s11
	s_and_b64 vcc, exec, s[42:43]
	global_load_lds_dwordx4 v194, s[68:69]
	s_mov_b32 m0, s12
	s_nop 0
	global_load_lds_dwordx4 v196, s[68:69]
	s_mov_b32 m0, s8
	s_nop 0
	global_load_lds_dwordx4 v194, s[56:57]
	s_mov_b32 m0, s13
	s_nop 0
	global_load_lds_dwordx4 v196, s[56:57]
	s_waitcnt lgkmcnt(0)
	s_barrier
	s_cbranch_vccnz .LBB0_1293
	s_waitcnt lgkmcnt(0)
	v_mfma_f32_16x16x32_bf16 v[62:65], v[146:149], v[174:177], v[62:65]
	v_mfma_f32_16x16x32_bf16 v[58:61], v[154:157], v[174:177], v[58:61]
	v_mfma_f32_16x16x32_bf16 v[46:49], v[146:149], v[170:173], v[46:49]
	v_mfma_f32_16x16x32_bf16 v[42:45], v[154:157], v[170:173], v[42:45]
	v_mfma_f32_16x16x32_bf16 v[30:33], v[146:149], v[166:169], v[30:33]
	v_mfma_f32_16x16x32_bf16 v[26:29], v[154:157], v[166:169], v[26:29]
	v_mfma_f32_16x16x32_bf16 v[14:17], v[146:149], v[162:165], v[14:17]
	v_mfma_f32_16x16x32_bf16 v[10:13], v[154:157], v[162:165], v[10:13]
	v_mfma_f32_16x16x32_bf16 v[62:65], v[150:153], v[190:193], v[62:65]
	v_mfma_f32_16x16x32_bf16 v[58:61], v[158:161], v[190:193], v[58:61]
	v_mfma_f32_16x16x32_bf16 v[46:49], v[150:153], v[186:189], v[46:49]
	v_mfma_f32_16x16x32_bf16 v[42:45], v[158:161], v[186:189], v[42:45]
	v_mfma_f32_16x16x32_bf16 v[30:33], v[150:153], v[182:185], v[30:33]
	v_mfma_f32_16x16x32_bf16 v[26:29], v[158:161], v[182:185], v[26:29]
	v_mfma_f32_16x16x32_bf16 v[14:17], v[150:153], v[178:181], v[14:17]
	v_mfma_f32_16x16x32_bf16 v[10:13], v[158:161], v[178:181], v[10:13]
	v_mfma_f32_16x16x32_bf16 v[54:57], v[130:133], v[174:177], v[54:57]
	v_mfma_f32_16x16x32_bf16 v[50:53], v[138:141], v[174:177], v[50:53]
	v_mfma_f32_16x16x32_bf16 v[38:41], v[130:133], v[170:173], v[38:41]
	v_mfma_f32_16x16x32_bf16 v[34:37], v[138:141], v[170:173], v[34:37]
	v_mfma_f32_16x16x32_bf16 v[22:25], v[130:133], v[166:169], v[22:25]
	v_mfma_f32_16x16x32_bf16 v[18:21], v[138:141], v[166:169], v[18:21]
	v_mfma_f32_16x16x32_bf16 v[6:9], v[130:133], v[162:165], v[6:9]
	v_mfma_f32_16x16x32_bf16 v[2:5], v[138:141], v[162:165], v[2:5]
	v_mfma_f32_16x16x32_bf16 v[54:57], v[134:137], v[190:193], v[54:57]
	v_mfma_f32_16x16x32_bf16 v[50:53], v[142:145], v[190:193], v[50:53]
	v_mfma_f32_16x16x32_bf16 v[38:41], v[134:137], v[186:189], v[38:41]
	v_mfma_f32_16x16x32_bf16 v[34:37], v[142:145], v[186:189], v[34:37]
	v_mfma_f32_16x16x32_bf16 v[22:25], v[134:137], v[182:185], v[22:25]
	v_mfma_f32_16x16x32_bf16 v[18:21], v[142:145], v[182:185], v[18:21]
	v_mfma_f32_16x16x32_bf16 v[6:9], v[134:137], v[178:181], v[6:9]
	v_mfma_f32_16x16x32_bf16 v[2:5], v[142:145], v[178:181], v[2:5]
.LBB0_1293:
	s_and_b64 vcc, s[34:35], s[58:59]
	v_cndmask_b32_e64 v131, v221, 0, vcc
	v_cndmask_b32_e32 v130, v220, v198, vcc
	v_lshl_add_u64 v[234:235], s[56:57], 0, v[130:131]
	v_add_u32_e32 v130, 0x18000, v229
	v_add_u32_e32 v142, 0x1c000, v229
	ds_read_b128 v[146:149], v130
	ds_read_b128 v[150:153], v130 offset:1024
	ds_read_b128 v[154:157], v130 offset:2048
	ds_read_b128 v[158:161], v130 offset:3072
	ds_read_b128 v[130:133], v142
	ds_read_b128 v[134:137], v142 offset:1024
	ds_read_b128 v[138:141], v142 offset:2048
	ds_read_b128 v[142:145], v142 offset:3072
	s_waitcnt lgkmcnt(0)
	ds_read_b128 v[174:177], v231 offset:32768
	ds_read_b128 v[190:193], v231 offset:33792
	ds_read_b128 v[170:173], v231 offset:34816
	ds_read_b128 v[186:189], v231 offset:35840
	ds_read_b128 v[166:169], v231 offset:36864
	ds_read_b128 v[182:185], v231 offset:37888
	ds_read_b128 v[162:165], v231 offset:38912
	ds_read_b128 v[178:181], v231 offset:39936
	s_waitcnt lgkmcnt(0)
	s_barrier
	v_mfma_f32_16x16x32_bf16 v[126:129], v[146:149], v[174:177], v[126:129]
	v_mfma_f32_16x16x32_bf16 v[122:125], v[154:157], v[174:177], v[122:125]
	v_mfma_f32_16x16x32_bf16 v[118:121], v[146:149], v[170:173], v[118:121]
	v_mfma_f32_16x16x32_bf16 v[110:113], v[154:157], v[170:173], v[110:113]
	v_mfma_f32_16x16x32_bf16 v[102:105], v[146:149], v[166:169], v[102:105]
	v_mfma_f32_16x16x32_bf16 v[94:97], v[154:157], v[166:169], v[94:97]
	v_mfma_f32_16x16x32_bf16 v[86:89], v[146:149], v[162:165], v[86:89]
	v_mfma_f32_16x16x32_bf16 v[78:81], v[154:157], v[162:165], v[78:81]
	v_mfma_f32_16x16x32_bf16 v[126:129], v[150:153], v[190:193], v[126:129]
	v_mfma_f32_16x16x32_bf16 v[122:125], v[158:161], v[190:193], v[122:125]
	v_mfma_f32_16x16x32_bf16 v[118:121], v[150:153], v[186:189], v[118:121]
	v_mfma_f32_16x16x32_bf16 v[110:113], v[158:161], v[186:189], v[110:113]
	v_mfma_f32_16x16x32_bf16 v[102:105], v[150:153], v[182:185], v[102:105]
	v_mfma_f32_16x16x32_bf16 v[94:97], v[158:161], v[182:185], v[94:97]
	v_mfma_f32_16x16x32_bf16 v[86:89], v[150:153], v[178:181], v[86:89]
	v_mfma_f32_16x16x32_bf16 v[78:81], v[158:161], v[178:181], v[78:81]
	v_mfma_f32_16x16x32_bf16 v[114:117], v[130:133], v[174:177], v[114:117]
	v_mfma_f32_16x16x32_bf16 v[106:109], v[138:141], v[174:177], v[106:109]
	v_mfma_f32_16x16x32_bf16 v[98:101], v[130:133], v[170:173], v[98:101]
	v_mfma_f32_16x16x32_bf16 v[90:93], v[138:141], v[170:173], v[90:93]
	v_mfma_f32_16x16x32_bf16 v[82:85], v[130:133], v[166:169], v[82:85]
	v_mfma_f32_16x16x32_bf16 v[74:77], v[138:141], v[166:169], v[74:77]
	v_mfma_f32_16x16x32_bf16 v[70:73], v[130:133], v[162:165], v[70:73]
	v_mfma_f32_16x16x32_bf16 v[66:69], v[138:141], v[162:165], v[66:69]
	v_mfma_f32_16x16x32_bf16 v[114:117], v[134:137], v[190:193], v[114:117]
	v_mfma_f32_16x16x32_bf16 v[106:109], v[142:145], v[190:193], v[106:109]
	v_mfma_f32_16x16x32_bf16 v[98:101], v[134:137], v[186:189], v[98:101]
	v_mfma_f32_16x16x32_bf16 v[90:93], v[142:145], v[186:189], v[90:93]
	v_mfma_f32_16x16x32_bf16 v[82:85], v[134:137], v[182:185], v[82:85]
	v_mfma_f32_16x16x32_bf16 v[74:77], v[142:145], v[182:185], v[74:77]
	v_mfma_f32_16x16x32_bf16 v[70:73], v[134:137], v[178:181], v[70:73]
	v_mfma_f32_16x16x32_bf16 v[66:69], v[142:145], v[178:181], v[66:69]
	s_waitcnt vmcnt(0)
	s_barrier
	s_and_b64 vcc, exec, s[42:43]
	s_cbranch_vccnz .LBB0_1295
	ds_read_b128 v[174:177], v231 offset:49152
	ds_read_b128 v[190:193], v231 offset:50176
	ds_read_b128 v[170:173], v231 offset:51200
	ds_read_b128 v[186:189], v231 offset:52224
	ds_read_b128 v[166:169], v231 offset:53248
	ds_read_b128 v[182:185], v231 offset:54272
	ds_read_b128 v[162:165], v231 offset:55296
	ds_read_b128 v[178:181], v231 offset:56320
.LBB0_1295:
	s_add_u32 s58, s52, 0x40000
	s_addc_u32 s59, s53, 0
	s_add_u32 s56, s56, 0x220000
	s_addc_u32 s57, s57, 0
	s_mov_b32 m0, s16
	s_add_u32 s52, s52, 0x44000
	global_load_lds_dwordx4 v194, s[58:59]
	s_mov_b32 m0, s17
	s_addc_u32 s53, s53, 0
	global_load_lds_dwordx4 v196, s[58:59]
	s_mov_b32 m0, s55
	s_and_b64 vcc, exec, s[42:43]
	global_load_lds_dwordx4 v194, s[52:53]
	s_mov_b32 m0, s60
	s_nop 0
	global_load_lds_dwordx4 v196, s[52:53]
	s_mov_b32 m0, s27
	s_nop 0
	global_load_lds_dwordx4 v194, s[56:57]
	s_mov_b32 m0, s54
	s_nop 0
	global_load_lds_dwordx4 v196, s[56:57]
	s_waitcnt lgkmcnt(0)
	s_barrier
	s_cbranch_vccnz .LBB0_1288
	s_waitcnt lgkmcnt(0)
	v_mfma_f32_16x16x32_bf16 v[62:65], v[146:149], v[174:177], v[62:65]
	v_mfma_f32_16x16x32_bf16 v[58:61], v[154:157], v[174:177], v[58:61]
	v_mfma_f32_16x16x32_bf16 v[46:49], v[146:149], v[170:173], v[46:49]
	v_mfma_f32_16x16x32_bf16 v[42:45], v[154:157], v[170:173], v[42:45]
	v_mfma_f32_16x16x32_bf16 v[30:33], v[146:149], v[166:169], v[30:33]
	v_mfma_f32_16x16x32_bf16 v[26:29], v[154:157], v[166:169], v[26:29]
	v_mfma_f32_16x16x32_bf16 v[14:17], v[146:149], v[162:165], v[14:17]
	v_mfma_f32_16x16x32_bf16 v[10:13], v[154:157], v[162:165], v[10:13]
	v_mfma_f32_16x16x32_bf16 v[62:65], v[150:153], v[190:193], v[62:65]
	v_mfma_f32_16x16x32_bf16 v[58:61], v[158:161], v[190:193], v[58:61]
	v_mfma_f32_16x16x32_bf16 v[46:49], v[150:153], v[186:189], v[46:49]
	v_mfma_f32_16x16x32_bf16 v[42:45], v[158:161], v[186:189], v[42:45]
	v_mfma_f32_16x16x32_bf16 v[30:33], v[150:153], v[182:185], v[30:33]
	v_mfma_f32_16x16x32_bf16 v[26:29], v[158:161], v[182:185], v[26:29]
	v_mfma_f32_16x16x32_bf16 v[14:17], v[150:153], v[178:181], v[14:17]
	v_mfma_f32_16x16x32_bf16 v[10:13], v[158:161], v[178:181], v[10:13]
	v_mfma_f32_16x16x32_bf16 v[54:57], v[130:133], v[174:177], v[54:57]
	v_mfma_f32_16x16x32_bf16 v[50:53], v[138:141], v[174:177], v[50:53]
	v_mfma_f32_16x16x32_bf16 v[38:41], v[130:133], v[170:173], v[38:41]
	v_mfma_f32_16x16x32_bf16 v[34:37], v[138:141], v[170:173], v[34:37]
	v_mfma_f32_16x16x32_bf16 v[22:25], v[130:133], v[166:169], v[22:25]
	v_mfma_f32_16x16x32_bf16 v[18:21], v[138:141], v[166:169], v[18:21]
	v_mfma_f32_16x16x32_bf16 v[6:9], v[130:133], v[162:165], v[6:9]
	v_mfma_f32_16x16x32_bf16 v[2:5], v[138:141], v[162:165], v[2:5]
	v_mfma_f32_16x16x32_bf16 v[54:57], v[134:137], v[190:193], v[54:57]
	v_mfma_f32_16x16x32_bf16 v[50:53], v[142:145], v[190:193], v[50:53]
	v_mfma_f32_16x16x32_bf16 v[38:41], v[134:137], v[186:189], v[38:41]
	v_mfma_f32_16x16x32_bf16 v[34:37], v[142:145], v[186:189], v[34:37]
	v_mfma_f32_16x16x32_bf16 v[22:25], v[134:137], v[182:185], v[22:25]
	v_mfma_f32_16x16x32_bf16 v[18:21], v[142:145], v[182:185], v[18:21]
	v_mfma_f32_16x16x32_bf16 v[6:9], v[134:137], v[178:181], v[6:9]
	v_mfma_f32_16x16x32_bf16 v[2:5], v[142:145], v[178:181], v[2:5]
	s_branch .LBB0_1288
